# LN1 and LN2: the wave that sums a sample row drops one prompt row, which another wave takes as its fifth row
# baseline (speedup 1.0000x reference)
.LBB0_1569:
	s_cmp_lt_i32 s56, 8
	s_cselect_b64 s[4:5], -1, 0
	s_and_b64 s[0:1], s[4:5], s[0:1]
	s_andn2_b64 vcc, exec, s[0:1]
	s_cbranch_vccnz .LBB0_1598
	v_lshl_add_u32 v33, s2, 3, v167
	s_movk_i32 s3, 0x2100
	v_cmp_gt_i32_e32 vcc, s3, v33
	s_and_saveexec_b64 s[8:9], vcc
	s_cbranch_execz .LBB0_1597
	s_lshr_b32 s10, s2, 1
	s_and_b32 s11, s2, 1
	s_mul_i32 s36, s10, 14
	s_lshl_b32 s3, s11, 7
	s_add_i32 s10, s10, s3
	s_mul_i32 s3, s11, 7
	s_add_i32 s36, s36, s3
	s_addk_i32 s36, 0xff
	v_cmp_eq_u32_e32 vcc, 0, v167
	v_add_u32_e32 v33, s36, v167
	v_mov_b32_e32 v0, s10
	s_nop 0
	v_cndmask_b32_e32 v33, v33, v0, vcc
	v_readlane_b32 s36, v239, 49
	v_and_b32_e32 v32, 63, v166
	v_readlane_b32 s48, v239, 61
	v_readlane_b32 s49, v239, 62
	s_add_u32 s10, s94, 0x8b00000
	v_mov_b32_e32 v35, 0
	v_or_b32_e32 v36, 0x100, v32
	v_or_b32_e32 v38, 0x140, v32
	v_or_b32_e32 v40, 0x180, v32
	v_or_b32_e32 v42, 0x1c0, v32
	v_readlane_b32 s50, v239, 63
	v_readlane_b32 s51, v238, 0
	s_mov_b64 s[20:21], s[48:49]
	s_addc_u32 s11, s95, 0
	s_waitcnt vmcnt(0)
	v_or_b32_e32 v0, 64, v32
	v_or_b32_e32 v2, 0x80, v32
	v_or_b32_e32 v4, 0xc0, v32
	s_mov_b64 s[22:23], s[50:51]
	v_lshlrev_b32_e32 v14, 4, v36
	v_mov_b32_e32 v15, v35
	v_lshlrev_b32_e32 v16, 4, v38
	v_mov_b32_e32 v17, v35
	v_lshlrev_b32_e32 v18, 4, v40
	v_mov_b32_e32 v19, v35
	v_lshlrev_b32_e32 v20, 4, v42
	v_mov_b32_e32 v21, v35
	s_add_u32 s14, s94, 0x100000
	v_lshlrev_b32_e32 v6, 2, v32
	v_lshlrev_b32_e32 v34, 4, v32
	v_lshlrev_b32_e32 v8, 2, v0
	v_lshlrev_b32_e32 v10, 2, v2
	v_lshlrev_b32_e32 v12, 2, v4
	v_lshl_add_u64 v[48:49], s[20:21], 0, v[14:15]
	v_lshl_add_u64 v[50:51], s[22:23], 0, v[14:15]
	v_lshlrev_b32_e32 v14, 2, v36
	v_lshl_add_u64 v[52:53], s[20:21], 0, v[16:17]
	v_lshl_add_u64 v[54:55], s[22:23], 0, v[16:17]
	v_lshlrev_b32_e32 v16, 2, v38
	v_lshl_add_u64 v[56:57], s[20:21], 0, v[18:19]
	v_lshl_add_u64 v[58:59], s[22:23], 0, v[18:19]
	v_lshlrev_b32_e32 v18, 2, v40
	v_lshl_add_u64 v[60:61], s[20:21], 0, v[20:21]
	v_lshl_add_u64 v[62:63], s[22:23], 0, v[20:21]
	v_lshlrev_b32_e32 v20, 2, v42
	v_lshlrev_b32_e32 v66, 4, v0
	v_mbcnt_lo_u32_b32 v0, -1, 0
	s_mov_b64 s[12:13], 0x100000
	s_addc_u32 s15, s95, 0
	s_lshl_b32 s3, s33, 3
	s_movk_i32 s19, 0x80
	v_lshl_add_u64 v[44:45], s[20:21], 0, v[34:35]
	v_lshl_add_u64 v[46:47], s[22:23], 0, v[34:35]
	v_lshl_add_u64 v[64:65], s[10:11], 0, v[34:35]
	s_mov_b64 s[16:17], 0
	s_movk_i32 s26, 0x2080
	s_movk_i32 s27, 0x1fff
	s_mov_b32 s18, 0x3f9837f0
	v_lshlrev_b32_e32 v68, 4, v2
	v_lshlrev_b32_e32 v70, 4, v4
	s_mov_b64 s[20:21], 0x200000
	s_mov_b64 s[22:23], 0x300000
	s_mov_b32 s4, 0
	v_mov_b32_e32 v37, 0x3727c5ac
	s_mov_b32 s28, 0x800000
	s_movk_i32 s29, 0x7fff
	s_mov_b32 s30, 0xffff0000
	v_lshlrev_b32_e32 v34, 1, v6
	v_lshlrev_b32_e32 v72, 1, v8
	v_lshlrev_b32_e32 v74, 1, v10
	v_lshlrev_b32_e32 v76, 1, v12
	v_lshlrev_b32_e32 v78, 1, v14
	v_lshlrev_b32_e32 v80, 1, v16
	v_lshlrev_b32_e32 v82, 1, v18
	v_lshlrev_b32_e32 v84, 1, v20
	s_movk_i32 s31, 0x20ff
	v_mbcnt_hi_u32_b32 v39, -1, v0
	v_readlane_b32 s37, v239, 50
	v_readlane_b32 s38, v239, 51
	v_readlane_b32 s39, v239, 52
	v_readlane_b32 s40, v239, 53
	v_readlane_b32 s41, v239, 54
	v_readlane_b32 s42, v239, 55
	v_readlane_b32 s43, v239, 56
	v_readlane_b32 s44, v239, 57
	v_readlane_b32 s45, v239, 58
	v_readlane_b32 s46, v239, 59
	v_readlane_b32 s47, v239, 60
	s_branch .LBB0_1573

.LBB0_1573:
	v_add_u32_e32 v0, 0xffffe800, v33
	v_cmp_gt_u32_e32 vcc, s19, v0
	v_mov_b32_e32 v1, 0x2080
	s_nop 0
	v_cndmask_b32_e32 v96, v33, v1, vcc
	v_cmp_le_i32_e32 vcc, s26, v33
	v_add_u32_e32 v0, 0xfffff780, v33
	s_nop 0
	v_cndmask_b32_e32 v96, v96, v0, vcc
	v_cmp_gt_i32_e32 vcc, s26, v96
	s_and_saveexec_b64 s[6:7], vcc
	s_xor_b64 s[6:7], exec, s[6:7]
	s_cbranch_execz .LBB0_1595
	v_cmp_lt_i32_e32 vcc, s27, v96
	v_lshlrev_b32_e32 v94, 4, v32
	v_lshlrev_b32_e32 v92, 4, v36
	v_lshlrev_b32_e32 v90, 4, v38
	v_lshlrev_b32_e32 v88, 4, v40
	v_lshlrev_b32_e32 v86, 4, v42
	s_and_saveexec_b64 s[24:25], vcc
	s_xor_b64 s[24:25], exec, s[24:25]
	s_cbranch_execz .LBB0_1576
	v_add_u32_e32 v0, 0xffffe000, v96
	v_mov_b32_e32 v1, v35
	v_readlane_b32 s36, v239, 17
	v_lshlrev_b64 v[98:99], 13, v[0:1]
	v_readlane_b32 s38, v239, 19
	v_readlane_b32 s39, v239, 20
	v_mov_b32_e32 v95, v35
	v_mov_b32_e32 v93, v35
	v_lshl_add_u64 v[24:25], s[38:39], 0, v[98:99]
	v_mov_b32_e32 v91, v35
	v_mov_b32_e32 v89, v35
	v_mov_b32_e32 v87, v35
	v_lshl_add_u64 v[196:197], s[14:15], 0, v[98:99]
	v_lshl_add_u64 v[0:1], v[24:25], 0, v[94:95]
	v_lshl_add_u64 v[16:17], v[24:25], 0, v[92:93]
	v_lshl_add_u64 v[20:21], v[24:25], 0, v[90:91]
	v_lshl_add_u64 v[26:27], v[24:25], 0, v[88:89]
	v_lshl_add_u64 v[28:29], v[24:25], 0, v[86:87]
	v_lshl_add_u64 v[110:111], v[196:197], 0, v[94:95]
	v_lshl_add_u64 v[114:115], v[196:197], 0, v[92:93]
	v_lshl_add_u64 v[118:119], v[196:197], 0, v[90:91]
	v_lshl_add_u64 v[154:155], v[196:197], 0, s[12:13]
	v_mov_b32_e32 v67, v35
	v_mov_b32_e32 v69, v35
	v_mov_b32_e32 v71, v35
	global_load_dwordx4 v[12:15], v[0:1], off
	global_load_dwordx4 v[8:11], v[0:1], off offset:1024
	global_load_dwordx4 v[4:7], v[0:1], off offset:2048
	s_nop 0
	global_load_dwordx4 v[0:3], v[0:1], off offset:3072
	s_nop 0
	global_load_dwordx4 v[16:19], v[16:17], off
	s_nop 0
	global_load_dwordx4 v[20:23], v[20:21], off
	s_nop 0
	global_load_dwordx4 v[24:27], v[26:27], off
	s_nop 0
	global_load_dwordx4 v[28:31], v[28:29], off
	s_nop 0
	global_load_dwordx4 v[98:101], v[110:111], off
	global_load_dwordx4 v[102:105], v[110:111], off offset:1024
	global_load_dwordx4 v[106:109], v[110:111], off offset:2048
	s_nop 0
	global_load_dwordx4 v[110:113], v[110:111], off offset:3072
	s_nop 0
	global_load_dwordx4 v[114:117], v[114:115], off
	s_nop 0
	global_load_dwordx4 v[118:121], v[118:119], off
	v_lshl_add_u64 v[122:123], v[196:197], 0, v[88:89]
	v_lshl_add_u64 v[126:127], v[196:197], 0, v[86:87]
	v_lshl_add_u64 v[130:131], v[154:155], 0, v[94:95]
	v_lshl_add_u64 v[134:135], v[154:155], 0, v[66:67]
	v_lshl_add_u64 v[138:139], v[154:155], 0, v[68:69]
	v_lshl_add_u64 v[142:143], v[154:155], 0, v[70:71]
	v_lshl_add_u64 v[146:147], v[154:155], 0, v[92:93]
	v_lshl_add_u64 v[150:151], v[154:155], 0, v[90:91]
	v_lshl_add_u64 v[188:189], v[196:197], 0, s[20:21]
	global_load_dwordx4 v[122:125], v[122:123], off
	s_nop 0
	global_load_dwordx4 v[126:129], v[126:127], off
	s_nop 0
	global_load_dwordx4 v[130:133], v[130:131], off
	s_nop 0
	global_load_dwordx4 v[134:137], v[134:135], off
	s_nop 0
	global_load_dwordx4 v[138:141], v[138:139], off
	s_nop 0
	global_load_dwordx4 v[142:145], v[142:143], off
	s_nop 0
	global_load_dwordx4 v[146:149], v[146:147], off
	s_nop 0
	global_load_dwordx4 v[150:153], v[150:151], off
	v_lshl_add_u64 v[156:157], v[154:155], 0, v[88:89]
	v_lshl_add_u64 v[158:159], v[154:155], 0, v[86:87]
	v_lshl_add_u64 v[162:163], v[188:189], 0, v[94:95]
	v_lshl_add_u64 v[168:169], v[188:189], 0, v[66:67]
	v_lshl_add_u64 v[172:173], v[188:189], 0, v[68:69]
	v_lshl_add_u64 v[176:177], v[188:189], 0, v[70:71]
	v_lshl_add_u64 v[180:181], v[188:189], 0, v[92:93]
	v_lshl_add_u64 v[184:185], v[188:189], 0, v[90:91]
	v_lshl_add_u64 v[224:225], v[196:197], 0, s[22:23]
	global_load_dwordx4 v[154:157], v[156:157], off
	s_nop 0
	global_load_dwordx4 v[158:161], v[158:159], off
	s_nop 0
	global_load_dwordx4 v[162:165], v[162:163], off
	s_nop 0
	global_load_dwordx4 v[168:171], v[168:169], off
	s_nop 0
	global_load_dwordx4 v[172:175], v[172:173], off
	s_nop 0
	global_load_dwordx4 v[176:179], v[176:177], off
	s_nop 0
	global_load_dwordx4 v[180:183], v[180:181], off
	s_nop 0
	global_load_dwordx4 v[184:187], v[184:185], off
	v_lshl_add_u64 v[190:191], v[188:189], 0, v[88:89]
	v_lshl_add_u64 v[192:193], v[188:189], 0, v[86:87]
	v_lshl_add_u64 v[196:197], v[224:225], 0, v[94:95]
	v_lshl_add_u64 v[200:201], v[224:225], 0, v[66:67]
	v_lshl_add_u64 v[204:205], v[224:225], 0, v[68:69]
	v_lshl_add_u64 v[212:213], v[224:225], 0, v[92:93]
	v_lshl_add_u64 v[216:217], v[224:225], 0, v[90:91]
	global_load_dwordx4 v[188:191], v[190:191], off
	s_nop 0
	global_load_dwordx4 v[192:195], v[192:193], off
	v_lshl_add_u64 v[208:209], v[224:225], 0, v[70:71]
	global_load_dwordx4 v[196:199], v[196:197], off
	v_lshl_add_u64 v[220:221], v[224:225], 0, v[88:89]
	global_load_dwordx4 v[200:203], v[200:201], off
	v_lshl_add_u64 v[224:225], v[224:225], 0, v[86:87]
	global_load_dwordx4 v[204:207], v[204:205], off
	v_readlane_b32 s37, v239, 18
	global_load_dwordx4 v[212:215], v[212:213], off
	v_readlane_b32 s40, v239, 21
	global_load_dwordx4 v[216:219], v[216:217], off
	v_readlane_b32 s41, v239, 22
	global_load_dwordx4 v[208:211], v[208:209], off
	v_readlane_b32 s42, v239, 23
	global_load_dwordx4 v[220:223], v[220:221], off
	v_readlane_b32 s43, v239, 24
	global_load_dwordx4 v[224:227], v[224:225], off
	v_readlane_b32 s44, v239, 25
	v_readlane_b32 s45, v239, 26
	v_readlane_b32 s46, v239, 27
	v_readlane_b32 s47, v239, 28
	v_readlane_b32 s48, v239, 29
	v_readlane_b32 s49, v239, 30
	v_readlane_b32 s50, v239, 31
	v_readlane_b32 s51, v239, 32
	s_waitcnt vmcnt(31)
	v_pk_fma_f32 v[14:15], v[14:15], s[18:19], v[100:101] op_sel_hi:[1,0,1]
	v_pk_fma_f32 v[12:13], v[12:13], s[18:19], v[98:99] op_sel_hi:[1,0,1]
	s_waitcnt vmcnt(30)
	v_pk_fma_f32 v[10:11], v[10:11], s[18:19], v[104:105] op_sel_hi:[1,0,1]
	v_pk_fma_f32 v[8:9], v[8:9], s[18:19], v[102:103] op_sel_hi:[1,0,1]
	s_waitcnt vmcnt(29)
	v_pk_fma_f32 v[6:7], v[6:7], s[18:19], v[108:109] op_sel_hi:[1,0,1]
	v_pk_fma_f32 v[4:5], v[4:5], s[18:19], v[106:107] op_sel_hi:[1,0,1]
	s_waitcnt vmcnt(27)
	v_pk_fma_f32 v[18:19], v[18:19], s[18:19], v[116:117] op_sel_hi:[1,0,1]
	v_pk_fma_f32 v[16:17], v[16:17], s[18:19], v[114:115] op_sel_hi:[1,0,1]
	s_waitcnt vmcnt(26)
	v_pk_fma_f32 v[22:23], v[22:23], s[18:19], v[120:121] op_sel_hi:[1,0,1]
	v_pk_fma_f32 v[20:21], v[20:21], s[18:19], v[118:119] op_sel_hi:[1,0,1]
	v_pk_fma_f32 v[2:3], v[2:3], s[18:19], v[112:113] op_sel_hi:[1,0,1]
	v_pk_fma_f32 v[0:1], v[0:1], s[18:19], v[110:111] op_sel_hi:[1,0,1]
	s_waitcnt vmcnt(25)
	v_pk_fma_f32 v[26:27], v[26:27], s[18:19], v[124:125] op_sel_hi:[1,0,1]
	v_pk_fma_f32 v[24:25], v[24:25], s[18:19], v[122:123] op_sel_hi:[1,0,1]
	s_waitcnt vmcnt(24)
	v_pk_fma_f32 v[30:31], v[30:31], s[18:19], v[128:129] op_sel_hi:[1,0,1]
	v_pk_fma_f32 v[28:29], v[28:29], s[18:19], v[126:127] op_sel_hi:[1,0,1]
	s_waitcnt vmcnt(23)
	v_pk_add_f32 v[14:15], v[14:15], v[132:133]
	v_pk_add_f32 v[12:13], v[12:13], v[130:131]
	s_waitcnt vmcnt(22)
	v_pk_add_f32 v[10:11], v[10:11], v[136:137]
	v_pk_add_f32 v[8:9], v[8:9], v[134:135]
	s_waitcnt vmcnt(21)
	v_pk_add_f32 v[6:7], v[6:7], v[140:141]
	v_pk_add_f32 v[4:5], v[4:5], v[138:139]
	s_waitcnt vmcnt(19)
	v_pk_add_f32 v[18:19], v[18:19], v[148:149]
	v_pk_add_f32 v[16:17], v[16:17], v[146:147]
	s_waitcnt vmcnt(18)
	v_pk_add_f32 v[22:23], v[22:23], v[152:153]
	v_pk_add_f32 v[20:21], v[20:21], v[150:151]
	v_pk_add_f32 v[2:3], v[2:3], v[144:145]
	v_pk_add_f32 v[0:1], v[0:1], v[142:143]
	s_waitcnt vmcnt(17)
	v_pk_add_f32 v[26:27], v[26:27], v[156:157]
	v_pk_add_f32 v[24:25], v[24:25], v[154:155]
	s_waitcnt vmcnt(16)
	v_pk_add_f32 v[30:31], v[30:31], v[160:161]
	v_pk_add_f32 v[28:29], v[28:29], v[158:159]
	s_waitcnt vmcnt(15)
	v_pk_add_f32 v[14:15], v[14:15], v[164:165]
	v_pk_add_f32 v[12:13], v[12:13], v[162:163]
	s_waitcnt vmcnt(14)
	v_pk_add_f32 v[10:11], v[10:11], v[170:171]
	v_pk_add_f32 v[8:9], v[8:9], v[168:169]
	s_waitcnt vmcnt(13)
	v_pk_add_f32 v[6:7], v[6:7], v[174:175]
	v_pk_add_f32 v[4:5], v[4:5], v[172:173]
	s_waitcnt vmcnt(11)
	v_pk_add_f32 v[98:99], v[18:19], v[182:183]
	v_pk_add_f32 v[100:101], v[16:17], v[180:181]
	s_waitcnt vmcnt(10)
	v_pk_add_f32 v[22:23], v[22:23], v[186:187]
	v_pk_add_f32 v[102:103], v[20:21], v[184:185]
	v_pk_add_f32 v[2:3], v[2:3], v[178:179]
	v_pk_add_f32 v[0:1], v[0:1], v[176:177]
	s_waitcnt vmcnt(9)
	v_pk_add_f32 v[26:27], v[26:27], v[190:191]
	v_pk_add_f32 v[24:25], v[24:25], v[188:189]
	s_waitcnt vmcnt(8)
	v_pk_add_f32 v[30:31], v[30:31], v[194:195]
	v_pk_add_f32 v[28:29], v[28:29], v[192:193]
	s_waitcnt vmcnt(7)
	v_pk_add_f32 v[112:113], v[14:15], v[198:199]
	v_pk_add_f32 v[114:115], v[12:13], v[196:197]
	s_waitcnt vmcnt(6)
	v_pk_add_f32 v[106:107], v[10:11], v[202:203]
	v_pk_add_f32 v[108:109], v[8:9], v[200:201]
	s_waitcnt vmcnt(5)
	v_pk_add_f32 v[20:21], v[6:7], v[206:207]
	v_pk_add_f32 v[10:11], v[4:5], v[204:205]
	s_waitcnt vmcnt(4)
	v_pk_add_f32 v[14:15], v[98:99], v[214:215]
	v_pk_add_f32 v[12:13], v[100:101], v[212:213]
	s_waitcnt vmcnt(3)
	v_pk_add_f32 v[8:9], v[22:23], v[218:219]
	v_pk_add_f32 v[22:23], v[102:103], v[216:217]
	s_waitcnt vmcnt(2)
	v_pk_add_f32 v[18:19], v[2:3], v[210:211]
	v_pk_add_f32 v[16:17], v[0:1], v[208:209]
	s_waitcnt vmcnt(1)
	v_pk_add_f32 v[6:7], v[26:27], v[222:223]
	v_pk_add_f32 v[4:5], v[24:25], v[220:221]
	s_waitcnt vmcnt(0)
	v_pk_add_f32 v[2:3], v[30:31], v[226:227]
	v_pk_add_f32 v[0:1], v[28:29], v[224:225]
	v_add_u32_e32 v196, 0xffffe000, v96
	v_mov_b32_e32 v197, 0
	v_lshlrev_b64 v[196:197], 13, v[196:197]
	v_lshl_add_u64 v[196:197], s[14:15], 0, v[196:197]
	v_lshl_add_u64 v[196:197], v[196:197], 0, v[94:95]
	s_mov_b32 vcc_lo, 0x400000
	s_mov_b32 vcc_hi, 0
	v_lshl_add_u64 v[198:199], v[196:197], 0, vcc
	s_mov_b32 vcc_lo, 0x401000
	v_lshl_add_u64 v[200:201], v[196:197], 0, vcc
	global_load_dwordx4 v[128:131], v[198:199], off
	global_load_dwordx4 v[132:135], v[198:199], off offset:1024
	global_load_dwordx4 v[136:139], v[198:199], off offset:2048
	global_load_dwordx4 v[140:143], v[198:199], off offset:3072
	global_load_dwordx4 v[144:147], v[200:201], off
	global_load_dwordx4 v[148:151], v[200:201], off offset:1024
	global_load_dwordx4 v[152:155], v[200:201], off offset:2048
	global_load_dwordx4 v[156:159], v[200:201], off offset:3072
	s_mov_b32 vcc_lo, 0x500000
	s_mov_b32 vcc_hi, 0
	v_lshl_add_u64 v[198:199], v[196:197], 0, vcc
	s_mov_b32 vcc_lo, 0x501000
	v_lshl_add_u64 v[200:201], v[196:197], 0, vcc
	global_load_dwordx4 v[160:163], v[198:199], off
	global_load_dwordx4 v[168:171], v[198:199], off offset:1024
	global_load_dwordx4 v[172:175], v[198:199], off offset:2048
	global_load_dwordx4 v[176:179], v[198:199], off offset:3072
	global_load_dwordx4 v[180:183], v[200:201], off
	global_load_dwordx4 v[184:187], v[200:201], off offset:1024
	global_load_dwordx4 v[188:191], v[200:201], off offset:2048
	global_load_dwordx4 v[192:195], v[200:201], off offset:3072
	s_waitcnt vmcnt(15)
	v_pk_add_f32 v[114:115], v[114:115], v[128:129]
	v_pk_add_f32 v[112:113], v[112:113], v[130:131]
	s_waitcnt vmcnt(14)
	v_pk_add_f32 v[108:109], v[108:109], v[132:133]
	v_pk_add_f32 v[106:107], v[106:107], v[134:135]
	s_waitcnt vmcnt(13)
	v_pk_add_f32 v[10:11], v[10:11], v[136:137]
	v_pk_add_f32 v[20:21], v[20:21], v[138:139]
	s_waitcnt vmcnt(12)
	v_pk_add_f32 v[16:17], v[16:17], v[140:141]
	v_pk_add_f32 v[18:19], v[18:19], v[142:143]
	s_waitcnt vmcnt(11)
	v_pk_add_f32 v[12:13], v[12:13], v[144:145]
	v_pk_add_f32 v[14:15], v[14:15], v[146:147]
	s_waitcnt vmcnt(10)
	v_pk_add_f32 v[22:23], v[22:23], v[148:149]
	v_pk_add_f32 v[8:9], v[8:9], v[150:151]
	s_waitcnt vmcnt(9)
	v_pk_add_f32 v[4:5], v[4:5], v[152:153]
	v_pk_add_f32 v[6:7], v[6:7], v[154:155]
	s_waitcnt vmcnt(8)
	v_pk_add_f32 v[0:1], v[0:1], v[156:157]
	v_pk_add_f32 v[2:3], v[2:3], v[158:159]
	s_waitcnt vmcnt(7)
	v_pk_add_f32 v[114:115], v[114:115], v[160:161]
	v_pk_add_f32 v[112:113], v[112:113], v[162:163]
	s_waitcnt vmcnt(6)
	v_pk_add_f32 v[108:109], v[108:109], v[168:169]
	v_pk_add_f32 v[106:107], v[106:107], v[170:171]
	s_waitcnt vmcnt(5)
	v_pk_add_f32 v[10:11], v[10:11], v[172:173]
	v_pk_add_f32 v[20:21], v[20:21], v[174:175]
	s_waitcnt vmcnt(4)
	v_pk_add_f32 v[16:17], v[16:17], v[176:177]
	v_pk_add_f32 v[18:19], v[18:19], v[178:179]
	s_waitcnt vmcnt(3)
	v_pk_add_f32 v[12:13], v[12:13], v[180:181]
	v_pk_add_f32 v[14:15], v[14:15], v[182:183]
	s_waitcnt vmcnt(2)
	v_pk_add_f32 v[22:23], v[22:23], v[184:185]
	v_pk_add_f32 v[8:9], v[8:9], v[186:187]
	s_waitcnt vmcnt(1)
	v_pk_add_f32 v[4:5], v[4:5], v[188:189]
	v_pk_add_f32 v[6:7], v[6:7], v[190:191]
	s_waitcnt vmcnt(0)
	v_pk_add_f32 v[0:1], v[0:1], v[192:193]
	v_pk_add_f32 v[2:3], v[2:3], v[194:195]
	s_mov_b32 vcc_lo, 0x600000
	s_mov_b32 vcc_hi, 0
	v_lshl_add_u64 v[198:199], v[196:197], 0, vcc
	s_mov_b32 vcc_lo, 0x601000
	v_lshl_add_u64 v[200:201], v[196:197], 0, vcc
	global_load_dwordx4 v[128:131], v[198:199], off
	global_load_dwordx4 v[132:135], v[198:199], off offset:1024
	global_load_dwordx4 v[136:139], v[198:199], off offset:2048
	global_load_dwordx4 v[140:143], v[198:199], off offset:3072
	global_load_dwordx4 v[144:147], v[200:201], off
	global_load_dwordx4 v[148:151], v[200:201], off offset:1024
	global_load_dwordx4 v[152:155], v[200:201], off offset:2048
	global_load_dwordx4 v[156:159], v[200:201], off offset:3072
	s_mov_b32 vcc_lo, 0x700000
	s_mov_b32 vcc_hi, 0
	v_lshl_add_u64 v[198:199], v[196:197], 0, vcc
	s_mov_b32 vcc_lo, 0x701000
	v_lshl_add_u64 v[200:201], v[196:197], 0, vcc
	global_load_dwordx4 v[160:163], v[198:199], off
	global_load_dwordx4 v[168:171], v[198:199], off offset:1024
	global_load_dwordx4 v[172:175], v[198:199], off offset:2048
	global_load_dwordx4 v[176:179], v[198:199], off offset:3072
	global_load_dwordx4 v[180:183], v[200:201], off
	global_load_dwordx4 v[184:187], v[200:201], off offset:1024
	global_load_dwordx4 v[188:191], v[200:201], off offset:2048
	global_load_dwordx4 v[192:195], v[200:201], off offset:3072
	s_waitcnt vmcnt(15)
	v_pk_add_f32 v[114:115], v[114:115], v[128:129]
	v_pk_add_f32 v[112:113], v[112:113], v[130:131]
	s_waitcnt vmcnt(14)
	v_pk_add_f32 v[108:109], v[108:109], v[132:133]
	v_pk_add_f32 v[106:107], v[106:107], v[134:135]
	s_waitcnt vmcnt(13)
	v_pk_add_f32 v[10:11], v[10:11], v[136:137]
	v_pk_add_f32 v[20:21], v[20:21], v[138:139]
	s_waitcnt vmcnt(12)
	v_pk_add_f32 v[16:17], v[16:17], v[140:141]
	v_pk_add_f32 v[18:19], v[18:19], v[142:143]
	s_waitcnt vmcnt(11)
	v_pk_add_f32 v[12:13], v[12:13], v[144:145]
	v_pk_add_f32 v[14:15], v[14:15], v[146:147]
	s_waitcnt vmcnt(10)
	v_pk_add_f32 v[22:23], v[22:23], v[148:149]
	v_pk_add_f32 v[8:9], v[8:9], v[150:151]
	s_waitcnt vmcnt(9)
	v_pk_add_f32 v[4:5], v[4:5], v[152:153]
	v_pk_add_f32 v[6:7], v[6:7], v[154:155]
	s_waitcnt vmcnt(8)
	v_pk_add_f32 v[0:1], v[0:1], v[156:157]
	v_pk_add_f32 v[2:3], v[2:3], v[158:159]
	s_waitcnt vmcnt(7)
	v_pk_add_f32 v[114:115], v[114:115], v[160:161]
	v_pk_add_f32 v[112:113], v[112:113], v[162:163]
	s_waitcnt vmcnt(6)
	v_pk_add_f32 v[108:109], v[108:109], v[168:169]
	v_pk_add_f32 v[106:107], v[106:107], v[170:171]
	s_waitcnt vmcnt(5)
	v_pk_add_f32 v[10:11], v[10:11], v[172:173]
	v_pk_add_f32 v[20:21], v[20:21], v[174:175]
	s_waitcnt vmcnt(4)
	v_pk_add_f32 v[16:17], v[16:17], v[176:177]
	v_pk_add_f32 v[18:19], v[18:19], v[178:179]
	s_waitcnt vmcnt(3)
	v_pk_add_f32 v[12:13], v[12:13], v[180:181]
	v_pk_add_f32 v[14:15], v[14:15], v[182:183]
	s_waitcnt vmcnt(2)
	v_pk_add_f32 v[22:23], v[22:23], v[184:185]
	v_pk_add_f32 v[8:9], v[8:9], v[186:187]
	s_waitcnt vmcnt(1)
	v_pk_add_f32 v[4:5], v[4:5], v[188:189]
	v_pk_add_f32 v[6:7], v[6:7], v[190:191]
	s_waitcnt vmcnt(0)
	v_pk_add_f32 v[0:1], v[0:1], v[192:193]
	v_pk_add_f32 v[2:3], v[2:3], v[194:195]
	v_mov_b32_e32 v101, v8
	v_mov_b32_e32 v100, v23
	v_mov_b32_e32 v8, v22
	v_mov_b32_e32 v102, v15
	v_mov_b32_e32 v104, v13
	v_mov_b32_e32 v111, v20
	v_mov_b32_e32 v110, v11
	v_mov_b32_e32 v20, v10
	v_mov_b32_e32 v26, v107
	v_mov_b32_e32 v24, v109
	v_mov_b32_e32 v27, v113
	v_mov_b32_e32 v107, v112
	v_mov_b32_e32 v25, v115
	v_mov_b32_e32 v109, v114

.LBB0_1819:
	s_cmp_lt_i32 s56, 11
	s_cselect_b64 s[4:5], -1, 0
	s_and_b64 s[0:1], s[4:5], s[0:1]
	s_andn2_b64 vcc, exec, s[0:1]
	s_cbranch_vccnz .LBB0_1829
	v_lshl_add_u32 v90, s2, 3, v167
	s_movk_i32 s0, 0x2100
	v_cmp_gt_i32_e32 vcc, s0, v90
	s_and_saveexec_b64 s[0:1], vcc
	s_cbranch_execz .LBB0_1829
	s_lshr_b32 s8, s2, 1
	s_and_b32 s9, s2, 1
	s_lshl_b32 s10, s9, 7
	s_add_i32 s10, s10, s8
	s_mul_i32 s11, s8, 14
	s_mul_i32 s9, s9, 7
	s_add_i32 s11, s11, s9
	s_addk_i32 s11, 0xff
	v_add_u32_e32 v90, s11, v167
	v_cmp_eq_u32_e32 vcc, 0, v167
	v_mov_b32_e32 v0, s10
	s_nop 1
	v_cndmask_b32_e32 v90, v90, v0, vcc
	v_readlane_b32 s8, v239, 0
	v_readlane_b32 s9, v239, 1
	v_readlane_b32 s10, v239, 2
	v_readlane_b32 s11, v239, 3
	v_readlane_b32 s12, v239, 4
	v_readlane_b32 s13, v239, 5
	s_waitcnt vmcnt(0)
	v_and_b32_e32 v0, 63, v166
	v_readlane_b32 s14, v239, 6
	v_readlane_b32 s15, v239, 7
	s_mov_b64 s[8:9], s[12:13]
	v_mov_b32_e32 v29, 0
	v_or_b32_e32 v8, 0x100, v0
	v_lshlrev_b32_e32 v28, 4, v0
	s_mov_b64 s[10:11], s[14:15]
	v_or_b32_e32 v10, 0x140, v0
	v_lshl_add_u64 v[30:31], s[8:9], 0, v[28:29]
	v_lshl_add_u64 v[32:33], s[10:11], 0, v[28:29]
	v_lshlrev_b32_e32 v28, 4, v8
	v_or_b32_e32 v12, 0x180, v0
	v_lshl_add_u64 v[34:35], s[8:9], 0, v[28:29]
	v_lshl_add_u64 v[36:37], s[10:11], 0, v[28:29]
	v_lshlrev_b32_e32 v28, 4, v10
	s_add_u32 s0, s92, 0x4000000
	v_or_b32_e32 v14, 0x1c0, v0
	v_lshl_add_u64 v[38:39], s[8:9], 0, v[28:29]
	v_lshl_add_u64 v[40:41], s[10:11], 0, v[28:29]
	v_lshlrev_b32_e32 v28, 4, v12
	s_addc_u32 s1, s93, 0
	v_lshl_add_u64 v[42:43], s[8:9], 0, v[28:29]
	v_lshl_add_u64 v[44:45], s[10:11], 0, v[28:29]
	v_lshlrev_b32_e32 v28, 4, v14
	s_add_u32 s2, s94, 0x800000
	v_or_b32_e32 v2, 64, v0
	v_or_b32_e32 v4, 0x80, v0
	v_or_b32_e32 v6, 0xc0, v0
	v_lshl_add_u64 v[46:47], s[8:9], 0, v[28:29]
	v_lshl_add_u64 v[48:49], s[10:11], 0, v[28:29]
	v_lshlrev_b32_e32 v28, 4, v0
	v_mbcnt_lo_u32_b32 v0, -1, 0
	s_addc_u32 s3, s95, 0
	s_lshl_b32 s7, s33, 3
	s_movk_i32 s26, 0x80
	s_mov_b64 s[4:5], 0
	s_movk_i32 s27, 0x2080
	s_movk_i32 s28, 0x1fff
	s_mov_b32 s6, 0x3f9837f0
	s_mov_b64 s[8:9], 0x100000
	v_lshlrev_b32_e32 v50, 4, v2
	v_lshlrev_b32_e32 v52, 4, v4
	v_lshlrev_b32_e32 v54, 4, v6
	s_mov_b64 s[10:11], 0x200000
	s_mov_b64 s[12:13], 0x300000
	s_mov_b64 s[14:15], 0x400000
	s_mov_b64 s[16:17], 0x500000
	s_mov_b64 s[18:19], 0x600000
	s_mov_b64 s[20:21], 0x700000
	v_mov_b32_e32 v91, 0x3727c5ac
	s_mov_b32 s29, 0x800000
	s_movk_i32 s30, 0x20ff
	v_lshlrev_b32_e32 v56, 4, v8
	v_lshlrev_b32_e32 v58, 4, v10
	v_lshlrev_b32_e32 v60, 4, v12
	v_lshlrev_b32_e32 v62, 4, v14
	v_mbcnt_hi_u32_b32 v92, -1, v0
	s_branch .LBB0_1824

.LBB0_1824:
	v_add_u32_e32 v0, 0xffffe800, v90
	v_cmp_gt_u32_e32 vcc, s26, v0
	v_mov_b32_e32 v1, 0x2080
	s_nop 0
	v_cndmask_b32_e32 v22, v90, v1, vcc
	v_cmp_le_i32_e32 vcc, s27, v90
	v_add_u32_e32 v0, 0xfffff780, v90
	s_nop 0
	v_cndmask_b32_e32 v22, v22, v0, vcc
	v_cmp_gt_i32_e32 vcc, s27, v22
	s_and_saveexec_b64 s[22:23], vcc
	s_cbranch_execz .LBB0_1823
	v_cmp_lt_i32_e32 vcc, s28, v22
	s_and_saveexec_b64 s[24:25], vcc
	s_xor_b64 s[24:25], exec, s[24:25]
	s_cbranch_execz .LBB0_1827
	v_add_u32_e32 v0, 0xffffe000, v22
	v_mov_b32_e32 v1, v29
	v_lshlrev_b64 v[0:1], 13, v[0:1]
	v_lshl_add_u64 v[2:3], s[0:1], 0, v[0:1]
	v_lshl_add_u64 v[16:17], v[2:3], 0, v[28:29]
	v_mov_b32_e32 v57, v29
	v_mov_b32_e32 v59, v29
	global_load_dwordx4 v[4:7], v[16:17], off
	global_load_dwordx4 v[8:11], v[16:17], off offset:1024
	global_load_dwordx4 v[12:15], v[16:17], off offset:2048
	global_load_dwordx4 v[24:27], v[16:17], off offset:3072
	v_lshl_add_u64 v[16:17], v[2:3], 0, v[56:57]
	v_lshl_add_u64 v[18:19], v[2:3], 0, v[58:59]
	global_load_dwordx4 v[64:67], v[16:17], off
	global_load_dwordx4 v[68:71], v[18:19], off
	v_mov_b32_e32 v61, v29
	v_lshl_add_u64 v[18:19], s[2:3], 0, v[0:1]
	v_lshl_add_u64 v[16:17], v[2:3], 0, v[60:61]
	v_mov_b32_e32 v63, v29
	v_lshl_add_u64 v[0:1], v[18:19], 0, v[28:29]
	v_lshl_add_u64 v[2:3], v[2:3], 0, v[62:63]
	global_load_dwordx4 v[72:75], v[16:17], off
	global_load_dwordx4 v[76:79], v[2:3], off
	global_load_dwordx4 v[80:83], v[0:1], off
	global_load_dwordx4 v[84:87], v[0:1], off offset:1024
	global_load_dwordx4 v[94:97], v[0:1], off offset:2048
	global_load_dwordx4 v[98:101], v[0:1], off offset:3072
	v_lshl_add_u64 v[0:1], v[18:19], 0, v[56:57]
	v_lshl_add_u64 v[2:3], v[18:19], 0, v[58:59]
	global_load_dwordx4 v[102:105], v[0:1], off
	global_load_dwordx4 v[106:109], v[2:3], off
	v_lshl_add_u64 v[0:1], v[18:19], 0, v[60:61]
	v_lshl_add_u64 v[2:3], v[18:19], 0, v[62:63]
	global_load_dwordx4 v[110:113], v[0:1], off
	global_load_dwordx4 v[114:117], v[2:3], off
	v_lshl_add_u64 v[0:1], v[18:19], 0, s[8:9]
	v_lshl_add_u64 v[2:3], v[0:1], 0, v[28:29]
	v_mov_b32_e32 v51, v29
	v_mov_b32_e32 v53, v29
	v_lshl_add_u64 v[16:17], v[0:1], 0, v[50:51]
	global_load_dwordx4 v[118:121], v[2:3], off
	global_load_dwordx4 v[122:125], v[16:17], off
	v_lshl_add_u64 v[2:3], v[0:1], 0, v[52:53]
	v_mov_b32_e32 v55, v29
	v_lshl_add_u64 v[16:17], v[0:1], 0, v[54:55]
	global_load_dwordx4 v[126:129], v[2:3], off
	global_load_dwordx4 v[130:133], v[16:17], off
	v_lshl_add_u64 v[2:3], v[0:1], 0, v[56:57]
	v_lshl_add_u64 v[16:17], v[0:1], 0, v[58:59]
	global_load_dwordx4 v[134:137], v[2:3], off
	global_load_dwordx4 v[138:141], v[16:17], off
	v_lshl_add_u64 v[2:3], v[0:1], 0, v[60:61]
	v_lshl_add_u64 v[0:1], v[0:1], 0, v[62:63]
	global_load_dwordx4 v[142:145], v[2:3], off
	global_load_dwordx4 v[146:149], v[0:1], off
	v_lshl_add_u64 v[0:1], v[18:19], 0, s[10:11]
	v_lshl_add_u64 v[2:3], v[0:1], 0, v[28:29]
	global_load_dwordx4 v[150:153], v[2:3], off
	v_lshl_add_u64 v[2:3], v[0:1], 0, v[50:51]
	global_load_dwordx4 v[154:157], v[2:3], off
	v_lshl_add_u64 v[2:3], v[0:1], 0, v[52:53]
	global_load_dwordx4 v[158:161], v[2:3], off
	v_lshl_add_u64 v[2:3], v[0:1], 0, v[54:55]
	global_load_dwordx4 v[162:165], v[2:3], off
	v_lshl_add_u64 v[2:3], v[0:1], 0, v[56:57]
	global_load_dwordx4 v[166:169], v[2:3], off
	v_lshl_add_u64 v[2:3], v[0:1], 0, v[58:59]
	global_load_dwordx4 v[170:173], v[2:3], off
	v_lshl_add_u64 v[2:3], v[0:1], 0, v[60:61]
	v_lshl_add_u64 v[0:1], v[0:1], 0, v[62:63]
	global_load_dwordx4 v[174:177], v[2:3], off
	v_lshl_add_u64 v[198:199], v[18:19], 0, s[18:19]
	global_load_dwordx4 v[0:3], v[0:1], off
	v_lshl_add_u64 v[178:179], v[198:199], 0, v[50:51]
	v_lshl_add_u64 v[182:183], v[198:199], 0, v[52:53]
	v_lshl_add_u64 v[186:187], v[198:199], 0, v[54:55]
	v_lshl_add_u64 v[190:191], v[198:199], 0, v[56:57]
	v_lshl_add_u64 v[194:195], v[198:199], 0, v[58:59]
	v_lshl_add_u64 v[200:201], v[198:199], 0, v[60:61]
	v_lshl_add_u64 v[202:203], v[198:199], 0, v[62:63]
	s_waitcnt vmcnt(23)
	v_pk_fma_f32 v[4:5], v[4:5], s[6:7], v[80:81] op_sel_hi:[1,0,1]
	v_pk_fma_f32 v[6:7], v[6:7], s[6:7], v[82:83] op_sel_hi:[1,0,1]
	s_waitcnt vmcnt(22)
	v_pk_fma_f32 v[10:11], v[10:11], s[6:7], v[86:87] op_sel_hi:[1,0,1]
	s_waitcnt vmcnt(20)
	v_pk_fma_f32 v[16:17], v[26:27], s[6:7], v[100:101] op_sel_hi:[1,0,1]
	v_pk_fma_f32 v[20:21], v[24:25], s[6:7], v[98:99] op_sel_hi:[1,0,1]
	s_waitcnt vmcnt(19)
	v_pk_fma_f32 v[24:25], v[66:67], s[6:7], v[104:105] op_sel_hi:[1,0,1]
	v_pk_fma_f32 v[26:27], v[64:65], s[6:7], v[102:103] op_sel_hi:[1,0,1]
	s_waitcnt vmcnt(18)
	v_pk_fma_f32 v[64:65], v[70:71], s[6:7], v[108:109] op_sel_hi:[1,0,1]
	v_pk_fma_f32 v[66:67], v[68:69], s[6:7], v[106:107] op_sel_hi:[1,0,1]
	s_waitcnt vmcnt(17)
	v_pk_fma_f32 v[68:69], v[74:75], s[6:7], v[112:113] op_sel_hi:[1,0,1]
	v_pk_fma_f32 v[70:71], v[72:73], s[6:7], v[110:111] op_sel_hi:[1,0,1]
	s_waitcnt vmcnt(16)
	v_pk_fma_f32 v[72:73], v[78:79], s[6:7], v[116:117] op_sel_hi:[1,0,1]
	v_pk_fma_f32 v[8:9], v[8:9], s[6:7], v[84:85] op_sel_hi:[1,0,1]
	v_pk_fma_f32 v[14:15], v[14:15], s[6:7], v[96:97] op_sel_hi:[1,0,1]
	v_pk_fma_f32 v[12:13], v[12:13], s[6:7], v[94:95] op_sel_hi:[1,0,1]
	v_pk_fma_f32 v[74:75], v[76:77], s[6:7], v[114:115] op_sel_hi:[1,0,1]
	s_waitcnt vmcnt(15)
	v_pk_add_f32 v[4:5], v[4:5], v[118:119]
	v_lshl_add_u64 v[102:103], v[18:19], 0, s[12:13]
	v_pk_add_f32 v[6:7], v[6:7], v[120:121]
	s_waitcnt vmcnt(12)
	v_pk_add_f32 v[76:77], v[20:21], v[130:131]
	v_pk_add_f32 v[10:11], v[10:11], v[124:125]
	s_waitcnt vmcnt(11)
	v_pk_add_f32 v[78:79], v[24:25], v[136:137]
	v_pk_add_f32 v[80:81], v[26:27], v[134:135]
	s_waitcnt vmcnt(10)
	v_pk_add_f32 v[82:83], v[64:65], v[140:141]
	v_pk_add_f32 v[84:85], v[66:67], v[138:139]
	s_waitcnt vmcnt(9)
	v_pk_add_f32 v[86:87], v[68:69], v[144:145]
	v_pk_add_f32 v[88:89], v[70:71], v[142:143]
	s_waitcnt vmcnt(8)
	v_pk_add_f32 v[94:95], v[72:73], v[148:149]
	v_lshl_add_u64 v[134:135], v[18:19], 0, s[14:15]
	v_pk_add_f32 v[8:9], v[8:9], v[122:123]
	v_pk_add_f32 v[14:15], v[14:15], v[128:129]
	v_pk_add_f32 v[12:13], v[12:13], v[126:127]
	v_pk_add_f32 v[16:17], v[16:17], v[132:133]
	v_pk_add_f32 v[20:21], v[74:75], v[146:147]
	s_waitcnt vmcnt(7)
	v_pk_add_f32 v[26:27], v[4:5], v[150:151]
	s_waitcnt vmcnt(4)
	v_pk_add_f32 v[74:75], v[76:77], v[162:163]
	s_waitcnt vmcnt(3)
	v_pk_add_f32 v[76:77], v[78:79], v[168:169]
	v_pk_add_f32 v[78:79], v[80:81], v[166:167]
	s_waitcnt vmcnt(2)
	v_pk_add_f32 v[80:81], v[82:83], v[172:173]
	v_pk_add_f32 v[82:83], v[84:85], v[170:171]
	v_lshl_add_u64 v[4:5], v[102:103], 0, v[50:51]
	s_waitcnt vmcnt(1)
	v_pk_add_f32 v[84:85], v[86:87], v[176:177]
	v_pk_add_f32 v[86:87], v[88:89], v[174:175]
	s_waitcnt vmcnt(0)
	v_pk_add_f32 v[88:89], v[94:95], v[2:3]
	v_lshl_add_u64 v[2:3], v[102:103], 0, v[28:29]
	v_lshl_add_u64 v[94:95], v[102:103], 0, v[52:53]
	v_lshl_add_u64 v[96:97], v[102:103], 0, v[54:55]
	v_lshl_add_u64 v[104:105], v[102:103], 0, v[56:57]
	v_lshl_add_u64 v[106:107], v[102:103], 0, v[58:59]
	v_lshl_add_u64 v[110:111], v[102:103], 0, v[60:61]
	v_lshl_add_u64 v[112:113], v[102:103], 0, v[62:63]
	v_lshl_add_u64 v[118:119], v[134:135], 0, v[28:29]
	v_pk_add_f32 v[24:25], v[6:7], v[152:153]
	v_pk_add_f32 v[64:65], v[10:11], v[156:157]
	v_pk_add_f32 v[66:67], v[8:9], v[154:155]
	v_pk_add_f32 v[68:69], v[14:15], v[160:161]
	v_pk_add_f32 v[70:71], v[12:13], v[158:159]
	v_pk_add_f32 v[72:73], v[16:17], v[164:165]
	global_load_dwordx4 v[6:9], v[2:3], off
	s_nop 0
	global_load_dwordx4 v[2:5], v[4:5], off
	s_nop 0
	global_load_dwordx4 v[14:17], v[94:95], off
	global_load_dwordx4 v[10:13], v[96:97], off
	s_nop 0
	global_load_dwordx4 v[94:97], v[104:105], off
	global_load_dwordx4 v[98:101], v[106:107], off
	s_nop 0
	global_load_dwordx4 v[102:105], v[110:111], off
	global_load_dwordx4 v[106:109], v[112:113], off
	v_lshl_add_u64 v[120:121], v[134:135], 0, v[50:51]
	global_load_dwordx4 v[110:113], v[118:119], off
	global_load_dwordx4 v[114:117], v[120:121], off
	v_lshl_add_u64 v[118:119], v[134:135], 0, v[52:53]
	v_lshl_add_u64 v[122:123], v[134:135], 0, v[54:55]
	v_lshl_add_u64 v[126:127], v[134:135], 0, v[56:57]
	v_lshl_add_u64 v[130:131], v[134:135], 0, v[58:59]
	v_lshl_add_u64 v[166:167], v[18:19], 0, s[16:17]
	global_load_dwordx4 v[118:121], v[118:119], off
	s_nop 0
	global_load_dwordx4 v[122:125], v[122:123], off
	s_nop 0
	global_load_dwordx4 v[126:129], v[126:127], off
	s_nop 0
	global_load_dwordx4 v[130:133], v[130:131], off
	v_lshl_add_u64 v[136:137], v[134:135], 0, v[60:61]
	v_lshl_add_u64 v[138:139], v[134:135], 0, v[62:63]
	v_lshl_add_u64 v[142:143], v[166:167], 0, v[28:29]
	v_lshl_add_u64 v[146:147], v[166:167], 0, v[50:51]
	v_lshl_add_u64 v[150:151], v[166:167], 0, v[52:53]
	v_lshl_add_u64 v[154:155], v[166:167], 0, v[54:55]
	v_lshl_add_u64 v[158:159], v[166:167], 0, v[56:57]
	v_lshl_add_u64 v[162:163], v[166:167], 0, v[58:59]
	global_load_dwordx4 v[134:137], v[136:137], off
	s_nop 0
	global_load_dwordx4 v[138:141], v[138:139], off
	s_nop 0
	global_load_dwordx4 v[142:145], v[142:143], off
	s_nop 0
	global_load_dwordx4 v[146:149], v[146:147], off
	s_nop 0
	global_load_dwordx4 v[150:153], v[150:151], off
	s_nop 0
	global_load_dwordx4 v[154:157], v[154:155], off
	s_nop 0
	global_load_dwordx4 v[158:161], v[158:159], off
	s_nop 0
	global_load_dwordx4 v[162:165], v[162:163], off
	v_lshl_add_u64 v[168:169], v[166:167], 0, v[60:61]
	v_lshl_add_u64 v[170:171], v[166:167], 0, v[62:63]
	v_lshl_add_u64 v[174:175], v[198:199], 0, v[28:29]
	v_lshl_add_u64 v[18:19], v[18:19], 0, s[20:21]
	global_load_dwordx4 v[166:169], v[168:169], off
	s_nop 0
	global_load_dwordx4 v[170:173], v[170:171], off
	s_nop 0
	global_load_dwordx4 v[174:177], v[174:175], off
	s_nop 0
	global_load_dwordx4 v[178:181], v[178:179], off
	s_nop 0
	global_load_dwordx4 v[182:185], v[182:183], off
	s_nop 0
	global_load_dwordx4 v[186:189], v[186:187], off
	s_nop 0
	global_load_dwordx4 v[190:193], v[190:191], off
	s_nop 0
	global_load_dwordx4 v[194:197], v[194:195], off
	v_lshl_add_u64 v[206:207], v[18:19], 0, v[28:29]
	v_lshl_add_u64 v[210:211], v[18:19], 0, v[50:51]
	v_lshl_add_u64 v[214:215], v[18:19], 0, v[52:53]
	v_lshl_add_u64 v[218:219], v[18:19], 0, v[54:55]
	v_lshl_add_u64 v[222:223], v[18:19], 0, v[56:57]
	v_lshl_add_u64 v[226:227], v[18:19], 0, v[58:59]
	global_load_dwordx4 v[198:201], v[200:201], off
	s_nop 0
	global_load_dwordx4 v[202:205], v[202:203], off
	v_lshl_add_u64 v[230:231], v[18:19], 0, v[60:61]
	global_load_dwordx4 v[206:209], v[206:207], off
	v_lshl_add_u64 v[18:19], v[18:19], 0, v[62:63]
	global_load_dwordx4 v[210:213], v[210:211], off
	v_pk_add_f32 v[0:1], v[20:21], v[0:1]
	global_load_dwordx4 v[214:217], v[214:215], off
	s_waitcnt vmcnt(34)
	v_pk_add_f32 v[8:9], v[24:25], v[8:9]
	global_load_dwordx4 v[218:221], v[218:219], off
	v_pk_add_f32 v[6:7], v[26:27], v[6:7]
	global_load_dwordx4 v[222:225], v[222:223], off
	s_waitcnt vmcnt(35)
	v_pk_add_f32 v[4:5], v[64:65], v[4:5]
	global_load_dwordx4 v[226:229], v[226:227], off
	v_pk_add_f32 v[2:3], v[66:67], v[2:3]
	global_load_dwordx4 v[230:233], v[230:231], off
	s_waitcnt vmcnt(36)
	v_pk_add_f32 v[16:17], v[68:69], v[16:17]
	global_load_dwordx4 v[234:237], v[18:19], off
	v_pk_add_f32 v[14:15], v[70:71], v[14:15]
	s_waitcnt vmcnt(36)
	v_pk_add_f32 v[12:13], v[72:73], v[12:13]
	v_pk_add_f32 v[10:11], v[74:75], v[10:11]
	s_waitcnt vmcnt(35)
	v_pk_add_f32 v[18:19], v[76:77], v[96:97]
	v_pk_add_f32 v[20:21], v[78:79], v[94:95]
	s_waitcnt vmcnt(34)
	v_pk_add_f32 v[24:25], v[80:81], v[100:101]
	v_pk_add_f32 v[26:27], v[82:83], v[98:99]
	s_waitcnt vmcnt(33)
	v_pk_add_f32 v[64:65], v[84:85], v[104:105]
	v_pk_add_f32 v[66:67], v[86:87], v[102:103]
	s_waitcnt vmcnt(32)
	v_pk_add_f32 v[68:69], v[88:89], v[108:109]
	v_pk_add_f32 v[0:1], v[0:1], v[106:107]
	s_waitcnt vmcnt(31)
	v_pk_add_f32 v[8:9], v[8:9], v[112:113]
	v_pk_add_f32 v[6:7], v[6:7], v[110:111]
	s_waitcnt vmcnt(30)
	v_pk_add_f32 v[4:5], v[4:5], v[116:117]
	v_pk_add_f32 v[2:3], v[2:3], v[114:115]
	s_waitcnt vmcnt(29)
	v_pk_add_f32 v[16:17], v[16:17], v[120:121]
	v_pk_add_f32 v[14:15], v[14:15], v[118:119]
	s_waitcnt vmcnt(28)
	v_pk_add_f32 v[12:13], v[12:13], v[124:125]
	v_pk_add_f32 v[10:11], v[10:11], v[122:123]
	s_waitcnt vmcnt(27)
	v_pk_add_f32 v[18:19], v[18:19], v[128:129]
	v_pk_add_f32 v[20:21], v[20:21], v[126:127]
	s_waitcnt vmcnt(26)
	v_pk_add_f32 v[24:25], v[24:25], v[132:133]
	v_pk_add_f32 v[26:27], v[26:27], v[130:131]
	s_waitcnt vmcnt(25)
	v_pk_add_f32 v[64:65], v[64:65], v[136:137]
	v_pk_add_f32 v[66:67], v[66:67], v[134:135]
	s_waitcnt vmcnt(24)
	v_pk_add_f32 v[68:69], v[68:69], v[140:141]
	v_pk_add_f32 v[0:1], v[0:1], v[138:139]
	s_waitcnt vmcnt(23)
	v_pk_add_f32 v[8:9], v[8:9], v[144:145]
	v_pk_add_f32 v[6:7], v[6:7], v[142:143]
	s_waitcnt vmcnt(22)
	v_pk_add_f32 v[4:5], v[4:5], v[148:149]
	v_pk_add_f32 v[2:3], v[2:3], v[146:147]
	s_waitcnt vmcnt(21)
	v_pk_add_f32 v[16:17], v[16:17], v[152:153]
	v_pk_add_f32 v[14:15], v[14:15], v[150:151]
	s_waitcnt vmcnt(20)
	v_pk_add_f32 v[12:13], v[12:13], v[156:157]
	v_pk_add_f32 v[10:11], v[10:11], v[154:155]
	s_waitcnt vmcnt(19)
	v_pk_add_f32 v[18:19], v[18:19], v[160:161]
	v_pk_add_f32 v[20:21], v[20:21], v[158:159]
	s_waitcnt vmcnt(18)
	v_pk_add_f32 v[24:25], v[24:25], v[164:165]
	v_pk_add_f32 v[26:27], v[26:27], v[162:163]
	s_waitcnt vmcnt(17)
	v_pk_add_f32 v[64:65], v[64:65], v[168:169]
	v_pk_add_f32 v[66:67], v[66:67], v[166:167]
	s_waitcnt vmcnt(16)
	v_pk_add_f32 v[68:69], v[68:69], v[172:173]
	v_pk_add_f32 v[0:1], v[0:1], v[170:171]
	s_waitcnt vmcnt(15)
	v_pk_add_f32 v[8:9], v[8:9], v[176:177]
	v_pk_add_f32 v[6:7], v[6:7], v[174:175]
	s_waitcnt vmcnt(14)
	v_pk_add_f32 v[4:5], v[4:5], v[180:181]
	v_pk_add_f32 v[2:3], v[2:3], v[178:179]
	s_waitcnt vmcnt(13)
	v_pk_add_f32 v[16:17], v[16:17], v[184:185]
	v_pk_add_f32 v[14:15], v[14:15], v[182:183]
	s_waitcnt vmcnt(12)
	v_pk_add_f32 v[12:13], v[12:13], v[188:189]
	v_pk_add_f32 v[10:11], v[10:11], v[186:187]
	s_waitcnt vmcnt(11)
	v_pk_add_f32 v[74:75], v[18:19], v[192:193]
	v_pk_add_f32 v[76:77], v[20:21], v[190:191]
	s_waitcnt vmcnt(10)
	v_pk_add_f32 v[24:25], v[24:25], v[196:197]
	v_pk_add_f32 v[26:27], v[26:27], v[194:195]
	s_waitcnt vmcnt(9)
	v_pk_add_f32 v[64:65], v[64:65], v[200:201]
	v_pk_add_f32 v[66:67], v[66:67], v[198:199]
	s_waitcnt vmcnt(8)
	v_pk_add_f32 v[68:69], v[68:69], v[204:205]
	v_pk_add_f32 v[78:79], v[0:1], v[202:203]
	s_waitcnt vmcnt(7)
	v_pk_add_f32 v[80:81], v[8:9], v[208:209]
	v_pk_add_f32 v[82:83], v[6:7], v[206:207]
	s_waitcnt vmcnt(6)
	v_pk_add_f32 v[70:71], v[4:5], v[212:213]
	v_pk_add_f32 v[72:73], v[2:3], v[210:211]
	s_waitcnt vmcnt(5)
	v_pk_add_f32 v[20:21], v[16:17], v[216:217]
	v_pk_add_f32 v[84:85], v[14:15], v[214:215]
	s_waitcnt vmcnt(4)
	v_pk_add_f32 v[18:19], v[12:13], v[220:221]
	v_pk_add_f32 v[16:17], v[10:11], v[218:219]
	s_waitcnt vmcnt(3)
	v_pk_add_f32 v[14:15], v[74:75], v[224:225]
	v_pk_add_f32 v[12:13], v[76:77], v[222:223]
	s_waitcnt vmcnt(2)
	v_pk_add_f32 v[8:9], v[24:25], v[228:229]
	v_pk_add_f32 v[10:11], v[26:27], v[226:227]
	s_waitcnt vmcnt(1)
	v_pk_add_f32 v[2:3], v[64:65], v[232:233]
	v_pk_add_f32 v[0:1], v[66:67], v[230:231]
	s_waitcnt vmcnt(0)
	v_pk_add_f32 v[6:7], v[68:69], v[236:237]
	v_pk_add_f32 v[4:5], v[78:79], v[234:235]
	v_add_u32_e32 v86, 0xffffe000, v22
	v_mov_b32_e32 v87, 0
	v_lshlrev_b64 v[86:87], 13, v[86:87]
	v_lshl_add_u64 v[86:87], s[2:3], 0, v[86:87]
	v_lshl_add_u64 v[86:87], v[86:87], 0, v[28:29]
	s_mov_b32 s40, 0x800000
	s_mov_b32 s41, 0
	v_lshl_add_u64 v[88:89], v[86:87], 0, s[40:41]
	s_mov_b32 s40, 0x801000
	v_lshl_add_u64 v[94:95], v[86:87], 0, s[40:41]
	global_load_dwordx4 v[96:99], v[88:89], off
	global_load_dwordx4 v[100:103], v[88:89], off offset:1024
	global_load_dwordx4 v[104:107], v[88:89], off offset:2048
	global_load_dwordx4 v[108:111], v[88:89], off offset:3072
	global_load_dwordx4 v[112:115], v[94:95], off
	global_load_dwordx4 v[116:119], v[94:95], off offset:1024
	global_load_dwordx4 v[120:123], v[94:95], off offset:2048
	global_load_dwordx4 v[124:127], v[94:95], off offset:3072
	s_mov_b32 s40, 0x900000
	s_mov_b32 s41, 0
	v_lshl_add_u64 v[88:89], v[86:87], 0, s[40:41]
	s_mov_b32 s40, 0x901000
	v_lshl_add_u64 v[94:95], v[86:87], 0, s[40:41]
	global_load_dwordx4 v[128:131], v[88:89], off
	global_load_dwordx4 v[132:135], v[88:89], off offset:1024
	global_load_dwordx4 v[136:139], v[88:89], off offset:2048
	global_load_dwordx4 v[140:143], v[88:89], off offset:3072
	global_load_dwordx4 v[144:147], v[94:95], off
	global_load_dwordx4 v[148:151], v[94:95], off offset:1024
	global_load_dwordx4 v[152:155], v[94:95], off offset:2048
	global_load_dwordx4 v[156:159], v[94:95], off offset:3072
	s_mov_b32 s40, 0xa00000
	s_mov_b32 s41, 0
	v_lshl_add_u64 v[88:89], v[86:87], 0, s[40:41]
	s_mov_b32 s40, 0xa01000
	v_lshl_add_u64 v[94:95], v[86:87], 0, s[40:41]
	global_load_dwordx4 v[160:163], v[88:89], off
	global_load_dwordx4 v[164:167], v[88:89], off offset:1024
	global_load_dwordx4 v[168:171], v[88:89], off offset:2048
	global_load_dwordx4 v[172:175], v[88:89], off offset:3072
	global_load_dwordx4 v[176:179], v[94:95], off
	global_load_dwordx4 v[180:183], v[94:95], off offset:1024
	global_load_dwordx4 v[184:187], v[94:95], off offset:2048
	global_load_dwordx4 v[188:191], v[94:95], off offset:3072
	s_mov_b32 s40, 0xb00000
	s_mov_b32 s41, 0
	v_lshl_add_u64 v[88:89], v[86:87], 0, s[40:41]
	s_mov_b32 s40, 0xb01000
	v_lshl_add_u64 v[94:95], v[86:87], 0, s[40:41]
	global_load_dwordx4 v[192:195], v[88:89], off
	global_load_dwordx4 v[196:199], v[88:89], off offset:1024
	global_load_dwordx4 v[200:203], v[88:89], off offset:2048
	global_load_dwordx4 v[204:207], v[88:89], off offset:3072
	global_load_dwordx4 v[208:211], v[94:95], off
	global_load_dwordx4 v[212:215], v[94:95], off offset:1024
	global_load_dwordx4 v[216:219], v[94:95], off offset:2048
	global_load_dwordx4 v[220:223], v[94:95], off offset:3072
	s_waitcnt vmcnt(31)
	v_pk_add_f32 v[82:83], v[82:83], v[96:97]
	v_pk_add_f32 v[80:81], v[80:81], v[98:99]
	s_waitcnt vmcnt(30)
	v_pk_add_f32 v[72:73], v[72:73], v[100:101]
	v_pk_add_f32 v[70:71], v[70:71], v[102:103]
	s_waitcnt vmcnt(29)
	v_pk_add_f32 v[84:85], v[84:85], v[104:105]
	v_pk_add_f32 v[20:21], v[20:21], v[106:107]
	s_waitcnt vmcnt(28)
	v_pk_add_f32 v[16:17], v[16:17], v[108:109]
	v_pk_add_f32 v[18:19], v[18:19], v[110:111]
	s_waitcnt vmcnt(27)
	v_pk_add_f32 v[12:13], v[12:13], v[112:113]
	v_pk_add_f32 v[14:15], v[14:15], v[114:115]
	s_waitcnt vmcnt(26)
	v_pk_add_f32 v[10:11], v[10:11], v[116:117]
	v_pk_add_f32 v[8:9], v[8:9], v[118:119]
	s_waitcnt vmcnt(25)
	v_pk_add_f32 v[0:1], v[0:1], v[120:121]
	v_pk_add_f32 v[2:3], v[2:3], v[122:123]
	s_waitcnt vmcnt(24)
	v_pk_add_f32 v[4:5], v[4:5], v[124:125]
	v_pk_add_f32 v[6:7], v[6:7], v[126:127]
	s_waitcnt vmcnt(23)
	v_pk_add_f32 v[82:83], v[82:83], v[128:129]
	v_pk_add_f32 v[80:81], v[80:81], v[130:131]
	s_waitcnt vmcnt(22)
	v_pk_add_f32 v[72:73], v[72:73], v[132:133]
	v_pk_add_f32 v[70:71], v[70:71], v[134:135]
	s_waitcnt vmcnt(21)
	v_pk_add_f32 v[84:85], v[84:85], v[136:137]
	v_pk_add_f32 v[20:21], v[20:21], v[138:139]
	s_waitcnt vmcnt(20)
	v_pk_add_f32 v[16:17], v[16:17], v[140:141]
	v_pk_add_f32 v[18:19], v[18:19], v[142:143]
	s_waitcnt vmcnt(19)
	v_pk_add_f32 v[12:13], v[12:13], v[144:145]
	v_pk_add_f32 v[14:15], v[14:15], v[146:147]
	s_waitcnt vmcnt(18)
	v_pk_add_f32 v[10:11], v[10:11], v[148:149]
	v_pk_add_f32 v[8:9], v[8:9], v[150:151]
	s_waitcnt vmcnt(17)
	v_pk_add_f32 v[0:1], v[0:1], v[152:153]
	v_pk_add_f32 v[2:3], v[2:3], v[154:155]
	s_waitcnt vmcnt(16)
	v_pk_add_f32 v[4:5], v[4:5], v[156:157]
	v_pk_add_f32 v[6:7], v[6:7], v[158:159]
	s_waitcnt vmcnt(15)
	v_pk_add_f32 v[82:83], v[82:83], v[160:161]
	v_pk_add_f32 v[80:81], v[80:81], v[162:163]
	s_waitcnt vmcnt(14)
	v_pk_add_f32 v[72:73], v[72:73], v[164:165]
	v_pk_add_f32 v[70:71], v[70:71], v[166:167]
	s_waitcnt vmcnt(13)
	v_pk_add_f32 v[84:85], v[84:85], v[168:169]
	v_pk_add_f32 v[20:21], v[20:21], v[170:171]
	s_waitcnt vmcnt(12)
	v_pk_add_f32 v[16:17], v[16:17], v[172:173]
	v_pk_add_f32 v[18:19], v[18:19], v[174:175]
	s_waitcnt vmcnt(11)
	v_pk_add_f32 v[12:13], v[12:13], v[176:177]
	v_pk_add_f32 v[14:15], v[14:15], v[178:179]
	s_waitcnt vmcnt(10)
	v_pk_add_f32 v[10:11], v[10:11], v[180:181]
	v_pk_add_f32 v[8:9], v[8:9], v[182:183]
	s_waitcnt vmcnt(9)
	v_pk_add_f32 v[0:1], v[0:1], v[184:185]
	v_pk_add_f32 v[2:3], v[2:3], v[186:187]
	s_waitcnt vmcnt(8)
	v_pk_add_f32 v[4:5], v[4:5], v[188:189]
	v_pk_add_f32 v[6:7], v[6:7], v[190:191]
	s_waitcnt vmcnt(7)
	v_pk_add_f32 v[82:83], v[82:83], v[192:193]
	v_pk_add_f32 v[80:81], v[80:81], v[194:195]
	s_waitcnt vmcnt(6)
	v_pk_add_f32 v[72:73], v[72:73], v[196:197]
	v_pk_add_f32 v[70:71], v[70:71], v[198:199]
	s_waitcnt vmcnt(5)
	v_pk_add_f32 v[84:85], v[84:85], v[200:201]
	v_pk_add_f32 v[20:21], v[20:21], v[202:203]
	s_waitcnt vmcnt(4)
	v_pk_add_f32 v[16:17], v[16:17], v[204:205]
	v_pk_add_f32 v[18:19], v[18:19], v[206:207]
	s_waitcnt vmcnt(3)
	v_pk_add_f32 v[12:13], v[12:13], v[208:209]
	v_pk_add_f32 v[14:15], v[14:15], v[210:211]
	s_waitcnt vmcnt(2)
	v_pk_add_f32 v[10:11], v[10:11], v[212:213]
	v_pk_add_f32 v[8:9], v[8:9], v[214:215]
	s_waitcnt vmcnt(1)
	v_pk_add_f32 v[0:1], v[0:1], v[216:217]
	v_pk_add_f32 v[2:3], v[2:3], v[218:219]
	s_waitcnt vmcnt(0)
	v_pk_add_f32 v[4:5], v[4:5], v[220:221]
	v_pk_add_f32 v[6:7], v[6:7], v[222:223]
	s_mov_b32 s40, 0xc00000
	s_mov_b32 s41, 0
	v_lshl_add_u64 v[88:89], v[86:87], 0, s[40:41]
	s_mov_b32 s40, 0xc01000
	v_lshl_add_u64 v[94:95], v[86:87], 0, s[40:41]
	global_load_dwordx4 v[96:99], v[88:89], off
	global_load_dwordx4 v[100:103], v[88:89], off offset:1024
	global_load_dwordx4 v[104:107], v[88:89], off offset:2048
	global_load_dwordx4 v[108:111], v[88:89], off offset:3072
	global_load_dwordx4 v[112:115], v[94:95], off
	global_load_dwordx4 v[116:119], v[94:95], off offset:1024
	global_load_dwordx4 v[120:123], v[94:95], off offset:2048
	global_load_dwordx4 v[124:127], v[94:95], off offset:3072
	s_mov_b32 s40, 0xd00000
	s_mov_b32 s41, 0
	v_lshl_add_u64 v[88:89], v[86:87], 0, s[40:41]
	s_mov_b32 s40, 0xd01000
	v_lshl_add_u64 v[94:95], v[86:87], 0, s[40:41]
	global_load_dwordx4 v[128:131], v[88:89], off
	global_load_dwordx4 v[132:135], v[88:89], off offset:1024
	global_load_dwordx4 v[136:139], v[88:89], off offset:2048
	global_load_dwordx4 v[140:143], v[88:89], off offset:3072
	global_load_dwordx4 v[144:147], v[94:95], off
	global_load_dwordx4 v[148:151], v[94:95], off offset:1024
	global_load_dwordx4 v[152:155], v[94:95], off offset:2048
	global_load_dwordx4 v[156:159], v[94:95], off offset:3072
	s_mov_b32 s40, 0xe00000
	s_mov_b32 s41, 0
	v_lshl_add_u64 v[88:89], v[86:87], 0, s[40:41]
	s_mov_b32 s40, 0xe01000
	v_lshl_add_u64 v[94:95], v[86:87], 0, s[40:41]
	global_load_dwordx4 v[160:163], v[88:89], off
	global_load_dwordx4 v[164:167], v[88:89], off offset:1024
	global_load_dwordx4 v[168:171], v[88:89], off offset:2048
	global_load_dwordx4 v[172:175], v[88:89], off offset:3072
	global_load_dwordx4 v[176:179], v[94:95], off
	global_load_dwordx4 v[180:183], v[94:95], off offset:1024
	global_load_dwordx4 v[184:187], v[94:95], off offset:2048
	global_load_dwordx4 v[188:191], v[94:95], off offset:3072
	s_mov_b32 s40, 0xf00000
	s_mov_b32 s41, 0
	v_lshl_add_u64 v[88:89], v[86:87], 0, s[40:41]
	s_mov_b32 s40, 0xf01000
	v_lshl_add_u64 v[94:95], v[86:87], 0, s[40:41]
	global_load_dwordx4 v[192:195], v[88:89], off
	global_load_dwordx4 v[196:199], v[88:89], off offset:1024
	global_load_dwordx4 v[200:203], v[88:89], off offset:2048
	global_load_dwordx4 v[204:207], v[88:89], off offset:3072
	global_load_dwordx4 v[208:211], v[94:95], off
	global_load_dwordx4 v[212:215], v[94:95], off offset:1024
	global_load_dwordx4 v[216:219], v[94:95], off offset:2048
	global_load_dwordx4 v[220:223], v[94:95], off offset:3072
	s_waitcnt vmcnt(31)
	v_pk_add_f32 v[82:83], v[82:83], v[96:97]
	v_pk_add_f32 v[80:81], v[80:81], v[98:99]
	s_waitcnt vmcnt(30)
	v_pk_add_f32 v[72:73], v[72:73], v[100:101]
	v_pk_add_f32 v[70:71], v[70:71], v[102:103]
	s_waitcnt vmcnt(29)
	v_pk_add_f32 v[84:85], v[84:85], v[104:105]
	v_pk_add_f32 v[20:21], v[20:21], v[106:107]
	s_waitcnt vmcnt(28)
	v_pk_add_f32 v[16:17], v[16:17], v[108:109]
	v_pk_add_f32 v[18:19], v[18:19], v[110:111]
	s_waitcnt vmcnt(27)
	v_pk_add_f32 v[12:13], v[12:13], v[112:113]
	v_pk_add_f32 v[14:15], v[14:15], v[114:115]
	s_waitcnt vmcnt(26)
	v_pk_add_f32 v[10:11], v[10:11], v[116:117]
	v_pk_add_f32 v[8:9], v[8:9], v[118:119]
	s_waitcnt vmcnt(25)
	v_pk_add_f32 v[0:1], v[0:1], v[120:121]
	v_pk_add_f32 v[2:3], v[2:3], v[122:123]
	s_waitcnt vmcnt(24)
	v_pk_add_f32 v[4:5], v[4:5], v[124:125]
	v_pk_add_f32 v[6:7], v[6:7], v[126:127]
	s_waitcnt vmcnt(23)
	v_pk_add_f32 v[82:83], v[82:83], v[128:129]
	v_pk_add_f32 v[80:81], v[80:81], v[130:131]
	s_waitcnt vmcnt(22)
	v_pk_add_f32 v[72:73], v[72:73], v[132:133]
	v_pk_add_f32 v[70:71], v[70:71], v[134:135]
	s_waitcnt vmcnt(21)
	v_pk_add_f32 v[84:85], v[84:85], v[136:137]
	v_pk_add_f32 v[20:21], v[20:21], v[138:139]
	s_waitcnt vmcnt(20)
	v_pk_add_f32 v[16:17], v[16:17], v[140:141]
	v_pk_add_f32 v[18:19], v[18:19], v[142:143]
	s_waitcnt vmcnt(19)
	v_pk_add_f32 v[12:13], v[12:13], v[144:145]
	v_pk_add_f32 v[14:15], v[14:15], v[146:147]
	s_waitcnt vmcnt(18)
	v_pk_add_f32 v[10:11], v[10:11], v[148:149]
	v_pk_add_f32 v[8:9], v[8:9], v[150:151]
	s_waitcnt vmcnt(17)
	v_pk_add_f32 v[0:1], v[0:1], v[152:153]
	v_pk_add_f32 v[2:3], v[2:3], v[154:155]
	s_waitcnt vmcnt(16)
	v_pk_add_f32 v[4:5], v[4:5], v[156:157]
	v_pk_add_f32 v[6:7], v[6:7], v[158:159]
	s_waitcnt vmcnt(15)
	v_pk_add_f32 v[82:83], v[82:83], v[160:161]
	v_pk_add_f32 v[80:81], v[80:81], v[162:163]
	s_waitcnt vmcnt(14)
	v_pk_add_f32 v[72:73], v[72:73], v[164:165]
	v_pk_add_f32 v[70:71], v[70:71], v[166:167]
	s_waitcnt vmcnt(13)
	v_pk_add_f32 v[84:85], v[84:85], v[168:169]
	v_pk_add_f32 v[20:21], v[20:21], v[170:171]
	s_waitcnt vmcnt(12)
	v_pk_add_f32 v[16:17], v[16:17], v[172:173]
	v_pk_add_f32 v[18:19], v[18:19], v[174:175]
	s_waitcnt vmcnt(11)
	v_pk_add_f32 v[12:13], v[12:13], v[176:177]
	v_pk_add_f32 v[14:15], v[14:15], v[178:179]
	s_waitcnt vmcnt(10)
	v_pk_add_f32 v[10:11], v[10:11], v[180:181]
	v_pk_add_f32 v[8:9], v[8:9], v[182:183]
	s_waitcnt vmcnt(9)
	v_pk_add_f32 v[0:1], v[0:1], v[184:185]
	v_pk_add_f32 v[2:3], v[2:3], v[186:187]
	s_waitcnt vmcnt(8)
	v_pk_add_f32 v[4:5], v[4:5], v[188:189]
	v_pk_add_f32 v[6:7], v[6:7], v[190:191]
	s_waitcnt vmcnt(7)
	v_pk_add_f32 v[82:83], v[82:83], v[192:193]
	v_pk_add_f32 v[80:81], v[80:81], v[194:195]
	s_waitcnt vmcnt(6)
	v_pk_add_f32 v[72:73], v[72:73], v[196:197]
	v_pk_add_f32 v[70:71], v[70:71], v[198:199]
	s_waitcnt vmcnt(5)
	v_pk_add_f32 v[84:85], v[84:85], v[200:201]
	v_pk_add_f32 v[20:21], v[20:21], v[202:203]
	s_waitcnt vmcnt(4)
	v_pk_add_f32 v[16:17], v[16:17], v[204:205]
	v_pk_add_f32 v[18:19], v[18:19], v[206:207]
	s_waitcnt vmcnt(3)
	v_pk_add_f32 v[12:13], v[12:13], v[208:209]
	v_pk_add_f32 v[14:15], v[14:15], v[210:211]
	s_waitcnt vmcnt(2)
	v_pk_add_f32 v[10:11], v[10:11], v[212:213]
	v_pk_add_f32 v[8:9], v[8:9], v[214:215]
	s_waitcnt vmcnt(1)
	v_pk_add_f32 v[0:1], v[0:1], v[216:217]
	v_pk_add_f32 v[2:3], v[2:3], v[218:219]
	s_waitcnt vmcnt(0)
	v_pk_add_f32 v[4:5], v[4:5], v[220:221]
	v_pk_add_f32 v[6:7], v[6:7], v[222:223]
	v_mov_b32_e32 v75, v8
	v_mov_b32_e32 v74, v11
	v_mov_b32_e32 v8, v10
	v_mov_b32_e32 v66, v15
	v_mov_b32_e32 v68, v13
	v_mov_b32_e32 v77, v20
	v_mov_b32_e32 v76, v85
	v_mov_b32_e32 v20, v84
	v_mov_b32_e32 v26, v71
	v_mov_b32_e32 v24, v73
	v_mov_b32_e32 v27, v81
	v_mov_b32_e32 v71, v80
	v_mov_b32_e32 v25, v83
	v_mov_b32_e32 v73, v82
